# hg_a: the two per-unit lambda-bias constant loads prefetched one unit ahead (next to the raw tile prefetch); the vmcnt(0) after the unit's first barrier removed
# speedup vs baseline: 1.0023x; 1.0023x over previous
; __device__ __forceinline__ float sigmf(float x) { return __builtin_amdgcn_rcpf(1.0f + __expf(-x)); }
; __device__ __forceinline__ void hg_a_prefetch(const bf16_t* Z, int unit, int tid, u32x4 (&pre)[6]) {
;     const int b = unit >> 9, h = (unit >> 6) & 7, n = unit & 63; const int tok0 = b * SEQ + n * 64;
; #pragma unroll
;     for (int q = 0; q < 6; ++q) { const int i = tid + q * NT; const int arr = i >> 10, row = (i >> 4) & 63, cc = i & 15; pre[q] = __builtin_nontemporal_load((const u32x4*)(Z + (size_t)(tok0 + row) * ZW + 2048 + 1024 * arr + h * 128 + 8 * cc)); }
; __device__ __forceinline__ void hg_a_unit(const Params& p, LAS unsigned char* lds, int unit, int next_unit, u32x4 (&pre)[6]) {
;     ...
;         const int d = tid & 127, sub = tid >> 7, hd = h * 128 + d;
;         const float lb = sigmf(((const float*)p.in[I_LB])[hd] - ((const float*)p.in[I_LB])[1024 + hd]), omlb = 1.0f - lb;
; __global__ void __launch_bounds__(NT, 2) mk_fwd(Params p) {
;     ...
;     { u32x4 pre[6]; if (bid < 2048) hg_a_prefetch((const bf16_t*)(wsl() + WS_Z), bid, threadIdx.x, pre); for (int u = bid; u < 2048; u += G) hg_a_unit(p, lds, u, u + G, pre); }
.LBB0_139:
	s_and_b64 vcc, exec, s[10:11]
	s_barrier
	s_cbranch_vccz .LBB0_156
	s_load_dwordx2 s[4:5], s[0:1], 0x108
	s_waitcnt vmcnt(0)
	v_lshrrev_b32_e32 v0, 4, v162
	s_mov_b32 s9, 0
	v_lshlrev_b32_e32 v2, 4, v162
	v_and_b32_e32 v32, 0xf0, v2
	s_waitcnt lgkmcnt(0)
	s_mov_b32 s3, s5
	s_mov_b32 s6, s4
	s_add_u32 s6, s6, 0x400000
	s_addc_u32 s7, s3, 0
	s_lshl_b32 s8, s2, 6
	s_and_b32 s3, s82, 0xfffff000
	s_and_b32 s8, s8, 0xfc0
	s_or_b32 s10, s3, s8
	v_or_b32_e32 v0, s10, v0
	s_movk_i32 s3, 0x3000
	v_mov_b64_e32 v[12:13], s[6:7]
	v_mad_i64_i32 v[0:1], s[6:7], v0, s3, v[12:13]
	s_lshl_b32 s6, s2, 2
	s_and_b32 s8, s6, 0x700
	v_mov_b32_e32 v33, 0
	v_lshl_add_u64 v[0:1], v[0:1], 0, s[8:9]
	v_lshl_add_u64 v[0:1], v[0:1], 0, v[32:33]
	s_movk_i32 s24, 0x1000
	v_add_co_u32_e32 v4, vcc, s24, v0
	s_movk_i32 s6, 0x2000
	s_nop 0
	v_addc_co_u32_e32 v5, vcc, 0, v1, vcc
	v_add_u32_e32 v2, 0x200, v162
	v_add_co_u32_e32 v14, vcc, s6, v0
	v_lshrrev_b32_e32 v0, 4, v2
	v_and_or_b32 v0, v0, 63, s10
	v_and_b32_e32 v2, 0x400, v2
	v_addc_co_u32_e32 v15, vcc, 0, v1, vcc
	v_mad_i64_i32 v[0:1], s[6:7], v0, s3, v[12:13]
	v_lshlrev_b32_e32 v2, 1, v2
	v_mov_b32_e32 v3, v33
	v_lshl_add_u64 v[0:1], v[0:1], 0, v[2:3]
	v_lshl_add_u64 v[0:1], v[0:1], 0, s[8:9]
	v_lshl_add_u64 v[0:1], v[0:1], 0, v[32:33]
	v_add_co_u32_e32 v6, vcc, s24, v0
	v_mov_b32_e32 v60, s4
	s_nop 0
	v_addc_co_u32_e32 v7, vcc, 0, v1, vcc
	global_load_dwordx4 v[8:11], v[6:7], off nt
	global_load_dwordx4 v[0:3], v[4:5], off offset:2048 nt
	v_add_u32_e32 v6, 0x600, v162
	v_lshrrev_b32_e32 v4, 4, v6
	v_and_or_b32 v4, v4, 63, s10
	v_and_b32_e32 v6, 0xc00, v6
	v_mad_i64_i32 v[4:5], s[6:7], v4, s3, v[12:13]
	v_lshlrev_b32_e32 v6, 1, v6
	v_mov_b32_e32 v7, v33
	v_lshl_add_u64 v[4:5], v[4:5], 0, v[6:7]
	v_lshl_add_u64 v[4:5], v[4:5], 0, s[8:9]
	v_lshl_add_u64 v[4:5], v[4:5], 0, v[32:33]
	v_add_co_u32_e32 v24, vcc, s24, v4
	v_mov_b32_e32 v61, s5
	s_nop 0
	v_addc_co_u32_e32 v25, vcc, 0, v5, vcc
	global_load_dwordx4 v[4:7], v[14:15], off offset:-4096 nt
	global_load_dwordx4 v[16:19], v[14:15], off nt
	v_add_u32_e32 v14, 0xa00, v162
	v_lshrrev_b32_e32 v15, 4, v14
	v_and_or_b32 v15, v15, 63, s10
	v_and_b32_e32 v14, 0xc00, v14
	v_mad_i64_i32 v[12:13], s[6:7], v15, s3, v[12:13]
	v_lshlrev_b32_e32 v14, 1, v14
	v_mov_b32_e32 v15, v33
	v_lshl_add_u64 v[12:13], v[12:13], 0, v[14:15]
	v_lshl_add_u64 v[12:13], v[12:13], 0, s[8:9]
	v_lshl_add_u64 v[12:13], v[12:13], 0, v[32:33]
	v_add_co_u32_e32 v26, vcc, s24, v12
	s_add_i32 s4, 0, 0x4400
	s_nop 0
	v_addc_co_u32_e32 v27, vcc, 0, v13, vcc
	global_load_dwordx4 v[12:15], v[24:25], off nt
	global_load_dwordx4 v[20:23], v[26:27], off nt
	s_load_dwordx2 s[10:11], s[0:1], 0x50
	s_add_i32 s5, 0, 0x8800
	s_movk_i32 s25, 0x400
	v_mov_b32_e32 v62, s5
	v_mov_b32_e32 v63, s4
	s_movk_i32 s26, 0x110
	s_movk_i32 s27, 0xfbff
	s_movk_i32 s28, 0x880
	s_mov_b32 s29, 0x800000
	s_mov_b32 s30, 0x3f317217
	s_mov_b32 s31, 0x7f800000
	v_mov_b32_e32 v64, 0x41b17218
	s_add_i32 s33, 0, 0x13800
	s_movk_i32 s34, 0x7fff
	s_mov_b32 s35, 0xffff0000
	s_movk_i32 s36, 0x90
	s_movk_i32 s37, 0x80
	s_movk_i32 s38, 0x1ff
	s_add_i32 s39, 0, 0x11400
	v_mov_b32_e32 v65, 1
	s_mov_b32 s40, s2
	s_waitcnt lgkmcnt(0)
	s_lshl_b32 s98, s40, 1
	s_and_b32 s98, s98, 0x380
	v_and_b32_e32 v202, 0x7f, v162
	v_or_b32_e32 v202, s98, v202
	v_lshlrev_b32_e32 v202, 2, v202
	v_add_u32_e32 v203, 0x1000, v202
	global_load_dword v200, v202, s[10:11]
	global_load_dword v201, v203, s[10:11]
	s_branch .LBB0_142

; #define LAS __attribute__((address_space(3)))
; __device__ __forceinline__ float bf2f(unsigned h) { return __uint_as_float(h << 16); }
; __device__ __forceinline__ float sigmf(float x) { return __builtin_amdgcn_rcpf(1.0f + __expf(-x)); }
; __device__ __forceinline__ void hg_a_unit(const Params& p, LAS unsigned char* lds, int unit, int next_unit, u32x4 (&pre)[6]) {
;     ...
;     for (int q = 0; q < 6; ++q) { const int i = tid + q * NT; const int arr = i >> 10, row = (i >> 4) & 63, cc = i & 15;
;         *(LAS u32x4*)((arr == 0 ? QD : (arr == 1 ? KI : VR)) + row * 136 + 8 * cc) = pre[q]; }
;     __syncthreads();
;     {
;         const int d = tid & 127, sub = tid >> 7, hd = h * 128 + d;
;         const float lb = sigmf(((const float*)p.in[I_LB])[hd] - ((const float*)p.in[I_LB])[1024 + hd]), omlb = 1.0f - lb;
;         float q[16], kq[16], cl[16]; unsigned short vv[16]; float run = 0.f;
; #pragma unroll
;         for (int i = 0; i < 16; ++i) { const int t = sub * 16 + i; const float f = bf2f(KI[t * 136 + d]); const float sg = sigmf(f);
;             run += __logf(lb + omlb * sg); cl[i] = run; kq[i] = omlb * (1.0f - sg); q[i] = bf2f(QD[t * 136 + d]); vv[i] = VR[t * 136 + d]; }
.LBB0_142:
	v_readfirstlane_b32 s12, v60
	v_readfirstlane_b32 s13, v61
	v_mov_b32_e32 v66, v162
	s_lshl_b32 s4, s40, 6
	v_and_b32_e32 v38, 0xfffffc00, v66
	v_lshlrev_b32_e32 v67, 3, v66
	v_cmp_eq_u32_e32 vcc, s25, v38
	v_and_b32_e32 v24, 0x78, v67
	v_bfe_u32 v35, v66, 4, 6
	v_cndmask_b32_e32 v25, v62, v63, vcc
	v_cmp_gt_u32_e32 vcc, s25, v66
	v_mul_u32_u24_e32 v26, 0x110, v35
	v_lshlrev_b32_e32 v34, 1, v24
	v_cndmask_b32_e64 v25, v25, 0, vcc
	v_add3_u32 v24, v25, v26, v34
	s_waitcnt vmcnt(3)
	ds_write_b128 v24, v[4:7]
	v_add_u32_e32 v24, 0x200, v66
	v_and_b32_e32 v40, 0xfffffc00, v24
	s_and_b32 s16, s4, 0xfc0
	v_cmp_eq_u32_e64 s[4:5], s25, v40
	v_bfe_u32 v41, v24, 4, 6
	s_lshl_b32 s6, s40, 3
	v_cndmask_b32_e64 v25, v62, v63, s[4:5]
	v_cmp_gt_u32_e64 s[4:5], s25, v24
	s_add_u32 s14, s12, 0x400000
	s_addc_u32 s15, s13, 0
	v_cndmask_b32_e64 v24, v25, 0, s[4:5]
	v_mul_u32_u24_e32 v25, 0x110, v41
	v_add3_u32 v24, v24, v25, v34
	ds_write_b128 v24, v[8:11]
	v_cndmask_b32_e32 v24, v62, v63, vcc
	v_cmp_lt_u32_e32 vcc, s27, v66
	s_lshl_b32 s4, s40, 1
	v_and_b32_e32 v39, 0x7f, v66
	v_cndmask_b32_e64 v24, v24, 0, vcc
	v_add3_u32 v24, v24, v26, v34
	ds_write_b128 v24, v[0:3]
	v_add_u32_e32 v24, 0x600, v66
	v_and_b32_e32 v42, 0xfffffc00, v24
	v_cmp_eq_u32_e32 vcc, s25, v42
	v_bfe_u32 v43, v24, 4, 6
	s_and_b32 s8, s4, 0x380
	v_cndmask_b32_e32 v25, v62, v63, vcc
	v_cmp_gt_u32_e32 vcc, s25, v24
	v_ashrrev_i32_e32 v45, 7, v66
	s_and_b32 s17, s6, 0xfffff000
	v_cndmask_b32_e64 v24, v25, 0, vcc
	v_mul_u32_u24_e32 v25, 0x110, v43
	v_add3_u32 v24, v24, v25, v34
	s_waitcnt vmcnt(1)
	ds_write_b128 v24, v[12:15]
	v_add_u32_e32 v24, 0x800, v66
	v_and_b32_e32 v25, 0xfffffc00, v24
	v_cmp_eq_u32_e32 vcc, s25, v25
	v_lshl_add_u32 v97, v39, 2, s33
	v_lshlrev_b32_e32 v44, 4, v45
	v_cndmask_b32_e32 v25, v62, v63, vcc
	v_cmp_gt_u32_e32 vcc, s25, v24
	v_readfirstlane_b32 s41, v66
	s_nop 0
	v_cndmask_b32_e64 v24, v25, 0, vcc
	v_add3_u32 v24, v24, v26, v34
	ds_write_b128 v24, v[16:19]
	v_add_u32_e32 v24, 0xa00, v66
	v_and_b32_e32 v36, 0xfffffc00, v24
	v_cmp_eq_u32_e32 vcc, s25, v36
	v_bfe_u32 v37, v24, 4, 6
	s_nop 0
	v_cndmask_b32_e32 v25, v62, v63, vcc
	v_cmp_gt_u32_e32 vcc, s25, v24
	s_nop 1
	v_cndmask_b32_e64 v24, v25, 0, vcc
	v_mul_u32_u24_e32 v25, 0x110, v37
	v_add3_u32 v24, v24, v25, v34
	s_waitcnt vmcnt(0)
	ds_write_b128 v24, v[20:23]
	v_or_b32_e32 v24, s8, v39
	v_lshlrev_b32_e32 v32, 2, v24
	s_waitcnt lgkmcnt(0)
	v_lshl_add_u64 v[24:25], s[10:11], 0, v[32:33]
	v_add_co_u32_e32 v24, vcc, s24, v24
	s_nop 1
	v_addc_co_u32_e32 v25, vcc, 0, v25, vcc
	s_barrier
	v_mov_b32_e32 v26, v200
	s_lshl_b32 s8, s8, 1
	v_mov_b32_e32 v24, v201
	v_mul_lo_u32 v25, v45, s28
	v_or_b32_e32 v25, v25, v39
	v_lshl_add_u32 v68, v25, 1, 0
	v_sub_f32_e32 v24, v26, v24
	ds_read_u16 v25, v68 offset:17408
	ds_read_u16 v26, v68 offset:17680
	ds_read_u16 v27, v68 offset:17952
	ds_read_u16 v29, v68 offset:18224
	ds_read_u16 v46, v68 offset:18496
	ds_read_u16 v47, v68 offset:18768
	ds_read_u16 v48, v68 offset:19040
	ds_read_u16 v49, v68 offset:19312
	v_mul_f32_e32 v24, 0xbfb8aa3b, v24
	s_waitcnt lgkmcnt(7)
	v_lshlrev_b32_e32 v25, 16, v25
	v_exp_f32_e32 v24, v24
	v_mul_f32_e32 v25, 0xbfb8aa3b, v25
	v_exp_f32_e32 v25, v25
	s_waitcnt lgkmcnt(6)
	v_lshlrev_b32_e32 v26, 16, v26
	v_add_f32_e32 v24, 1.0, v24
	v_rcp_f32_e32 v57, v24
	v_add_f32_e32 v24, 1.0, v25
	v_rcp_f32_e32 v25, v24
	v_mul_f32_e32 v26, 0xbfb8aa3b, v26
	v_sub_f32_e32 v32, 1.0, v57
	v_exp_f32_e32 v26, v26
	v_fma_f32 v24, v32, v25, v57
	v_cmp_gt_f32_e32 vcc, s29, v24
	s_waitcnt lgkmcnt(5)
	v_lshlrev_b32_e32 v27, 16, v27
	v_mul_f32_e32 v27, 0xbfb8aa3b, v27
	v_cndmask_b32_e64 v28, 0, 32, vcc
	v_ldexp_f32 v24, v24, v28
	v_log_f32_e32 v24, v24
	v_exp_f32_e32 v27, v27
	s_waitcnt lgkmcnt(4)
	v_lshlrev_b32_e32 v29, 16, v29
	v_mul_f32_e32 v29, 0xbfb8aa3b, v29
	v_mul_f32_e32 v28, 0x3f317217, v24
	v_fma_f32 v28, v24, s30, -v28
	v_fmac_f32_e32 v28, 0x3377d1cf, v24
	v_fmac_f32_e32 v28, 0x3f317217, v24
	v_cmp_lt_f32_e64 s[4:5], |v24|, s31
	v_add_f32_e32 v27, 1.0, v27
	v_exp_f32_e32 v29, v29
	v_cndmask_b32_e64 v24, v24, v28, s[4:5]
	v_cndmask_b32_e32 v28, 0, v64, vcc
	v_sub_f32_e32 v24, v24, v28
	v_add_f32_e32 v28, 0, v24
	v_add_f32_e32 v24, 1.0, v26
	v_rcp_f32_e32 v24, v24
	ds_read_u16 v26, v68
	ds_read_u16 v30, v68 offset:272
	ds_read_u16 v50, v68 offset:544
	ds_read_u16 v51, v68 offset:816
	ds_read_u16 v52, v68 offset:1088
	ds_read_u16 v53, v68 offset:1360
	ds_read_u16 v54, v68 offset:1632
	ds_read_u16 v55, v68 offset:1904
	s_waitcnt lgkmcnt(7)
	v_lshlrev_b32_e32 v56, 16, v26
	s_waitcnt lgkmcnt(6)
	v_lshlrev_b32_e32 v73, 16, v30
	v_fma_f32 v26, v32, v24, v57
	v_cmp_gt_f32_e32 vcc, s29, v26
	v_lshlrev_b32_e32 v47, 16, v47
	v_mul_f32_e32 v47, 0xbfb8aa3b, v47
	v_cndmask_b32_e64 v31, 0, 32, vcc
	v_ldexp_f32 v26, v26, v31
	v_log_f32_e32 v26, v26
	v_exp_f32_e32 v47, v47
	v_lshlrev_b32_e32 v49, 16, v49
	v_mul_f32_e32 v49, 0xbfb8aa3b, v49
	v_mul_f32_e32 v31, 0x3f317217, v26
	v_fma_f32 v58, v26, s30, -v31
	v_rcp_f32_e32 v31, v27
	v_fmac_f32_e32 v58, 0x3377d1cf, v26
	v_fmac_f32_e32 v58, 0x3f317217, v26
	v_cmp_lt_f32_e64 s[4:5], |v26|, s31
	v_fma_f32 v27, v32, v31, v57
	v_exp_f32_e32 v49, v49
	v_cndmask_b32_e64 v26, v26, v58, s[4:5]
	v_cmp_gt_f32_e64 s[4:5], s29, v27
	s_waitcnt lgkmcnt(3)
	v_lshlrev_b32_e32 v70, 16, v52
	s_waitcnt lgkmcnt(2)
	v_lshlrev_b32_e32 v71, 16, v53
	v_cndmask_b32_e64 v58, 0, 32, s[4:5]
	v_ldexp_f32 v27, v27, v58
	v_log_f32_e32 v27, v27
	v_cndmask_b32_e32 v58, 0, v64, vcc
	v_sub_f32_e32 v58, v26, v58
	v_lshlrev_b32_e32 v72, 16, v51
	v_mul_f32_e32 v26, 0x3f317217, v27
	v_fma_f32 v26, v27, s30, -v26
	v_fmac_f32_e32 v26, 0x3377d1cf, v27
	v_fmac_f32_e32 v26, 0x3f317217, v27
	v_cmp_lt_f32_e64 vcc, |v27|, s31
	s_waitcnt lgkmcnt(1)
; __device__ __forceinline__ float bf2f(unsigned h) { return __uint_as_float(h << 16); }
; __device__ __forceinline__ float sigmf(float x) { return __builtin_amdgcn_rcpf(1.0f + __expf(-x)); }
; __device__ __forceinline__ void hg_a_unit(const Params& p, LAS unsigned char* lds, int unit, int next_unit, u32x4 (&pre)[6]) {
;     ...
;         for (int i = 0; i < 16; ++i) { const int t = sub * 16 + i; const float f = bf2f(KI[t * 136 + d]); const float sg = sigmf(f);
;             run += __logf(lb + omlb * sg); cl[i] = run; kq[i] = omlb * (1.0f - sg); q[i] = bf2f(QD[t * 136 + d]); vv[i] = VR[t * 136 + d]; }
	v_lshlrev_b32_e32 v69, 16, v54
	s_waitcnt lgkmcnt(0)
	v_lshlrev_b32_e32 v83, 16, v55
	v_cndmask_b32_e32 v26, v27, v26, vcc
	v_add_f32_e32 v27, 1.0, v29
	v_rcp_f32_e32 v30, v27
	v_cndmask_b32_e64 v27, 0, v64, s[4:5]
	v_sub_f32_e32 v59, v26, v27
	v_lshlrev_b32_e32 v29, 16, v50
	v_fma_f32 v26, v32, v30, v57
	v_cmp_gt_f32_e32 vcc, s29, v26
	v_pk_add_f32 v[24:25], v[24:25], 1.0 op_sel_hi:[1,0] neg_lo:[1,0] neg_hi:[1,0]
	v_pk_add_f32 v[30:31], v[30:31], 1.0 op_sel_hi:[1,0] neg_lo:[1,0] neg_hi:[1,0]
	v_cndmask_b32_e64 v27, 0, 32, vcc
	v_ldexp_f32 v26, v26, v27
	v_lshlrev_b32_e32 v27, 16, v46
	v_mul_f32_e32 v27, 0xbfb8aa3b, v27
	v_exp_f32_e32 v27, v27
	v_log_f32_e32 v26, v26
	v_pk_mul_f32 v[24:25], v[32:33], v[24:25] op_sel_hi:[0,1]
	v_pk_mul_f32 v[30:31], v[32:33], v[30:31] op_sel_hi:[0,1]
	v_add_f32_e32 v27, 1.0, v27
	v_mul_f32_e32 v46, 0x3f317217, v26
	v_rcp_f32_e32 v27, v27
	v_fma_f32 v46, v26, s30, -v46
	v_fmac_f32_e32 v46, 0x3377d1cf, v26
	v_fmac_f32_e32 v46, 0x3f317217, v26
	v_cmp_lt_f32_e64 s[4:5], |v26|, s31
	s_nop 1
	v_cndmask_b32_e64 v26, v26, v46, s[4:5]
	v_fma_f32 v46, v32, v27, v57
	v_cmp_gt_f32_e64 s[4:5], s29, v46
	s_nop 1
	v_cndmask_b32_e64 v50, 0, 32, s[4:5]
	v_ldexp_f32 v46, v46, v50
	v_log_f32_e32 v46, v46
	v_cndmask_b32_e32 v50, 0, v64, vcc
	v_sub_f32_e32 v74, v26, v50
	v_mul_f32_e32 v26, 0x3f317217, v46
	v_fma_f32 v26, v46, s30, -v26
	v_fmac_f32_e32 v26, 0x3377d1cf, v46
	v_fmac_f32_e32 v26, 0x3f317217, v46
	v_cmp_lt_f32_e64 vcc, |v46|, s31
	s_nop 1
	v_cndmask_b32_e32 v46, v46, v26, vcc
	v_add_f32_e32 v26, 1.0, v47
	v_rcp_f32_e32 v26, v26
	v_cndmask_b32_e64 v47, 0, v64, s[4:5]
	v_sub_f32_e32 v76, v46, v47
	v_fma_f32 v46, v32, v26, v57
	v_cmp_gt_f32_e32 vcc, s29, v46
	v_pk_add_f32 v[26:27], v[26:27], 1.0 op_sel_hi:[1,0] neg_lo:[1,0] neg_hi:[1,0]
	s_nop 0
	v_cndmask_b32_e64 v47, 0, 32, vcc
	v_ldexp_f32 v46, v46, v47
	v_lshlrev_b32_e32 v47, 16, v48
	v_mul_f32_e32 v47, 0xbfb8aa3b, v47
	v_exp_f32_e32 v47, v47
	v_log_f32_e32 v46, v46
	v_pk_mul_f32 v[26:27], v[32:33], v[26:27] op_sel_hi:[0,1]
	v_add_f32_e32 v47, 1.0, v47
	v_mul_f32_e32 v48, 0x3f317217, v46
	v_rcp_f32_e32 v47, v47
	v_fma_f32 v48, v46, s30, -v48
	v_fmac_f32_e32 v48, 0x3377d1cf, v46
	v_fmac_f32_e32 v48, 0x3f317217, v46
	v_cmp_lt_f32_e64 s[4:5], |v46|, s31
	s_nop 1
	v_cndmask_b32_e64 v46, v46, v48, s[4:5]
	v_fma_f32 v48, v32, v47, v57
	v_cmp_gt_f32_e64 s[4:5], s29, v48
	s_nop 1
	v_cndmask_b32_e64 v50, 0, 32, s[4:5]
	v_ldexp_f32 v48, v48, v50
	v_log_f32_e32 v48, v48
	v_cndmask_b32_e32 v50, 0, v64, vcc
	v_sub_f32_e32 v77, v46, v50
	v_mul_f32_e32 v46, 0x3f317217, v48
	v_fma_f32 v46, v48, s30, -v46
	v_fmac_f32_e32 v46, 0x3377d1cf, v48
	v_fmac_f32_e32 v46, 0x3f317217, v48
	v_cmp_lt_f32_e64 vcc, |v48|, s31
	s_nop 1
	v_cndmask_b32_e32 v48, v48, v46, vcc
	v_add_f32_e32 v46, 1.0, v49
	v_rcp_f32_e32 v46, v46
	v_cndmask_b32_e64 v49, 0, v64, s[4:5]
	v_sub_f32_e32 v78, v48, v49
	v_fma_f32 v48, v32, v46, v57
	v_cmp_gt_f32_e32 vcc, s29, v48
	v_pk_add_f32 v[46:47], v[46:47], 1.0 op_sel_hi:[1,0] neg_lo:[1,0] neg_hi:[1,0]
	s_nop 0
	v_cndmask_b32_e64 v49, 0, 32, vcc
	v_ldexp_f32 v48, v48, v49
	ds_read_u16 v49, v68 offset:19584
	ds_read_u16 v50, v68 offset:19856
	ds_read_u16 v52, v68 offset:20128
	ds_read_u16 v53, v68 offset:20400
	ds_read_u16 v75, v68 offset:20672
	ds_read_u16 v79, v68 offset:20944
	ds_read_u16 v80, v68 offset:21216
	ds_read_u16 v81, v68 offset:21488
	s_waitcnt lgkmcnt(7)
	v_lshlrev_b32_e32 v49, 16, v49
	v_mul_f32_e32 v49, 0xbfb8aa3b, v49
	v_log_f32_e32 v48, v48
	v_exp_f32_e32 v49, v49
	s_waitcnt lgkmcnt(6)
	v_lshlrev_b32_e32 v50, 16, v50
	v_mul_f32_e32 v50, 0xbfb8aa3b, v50
	v_mul_f32_e32 v51, 0x3f317217, v48
	v_add_f32_e32 v49, 1.0, v49
	v_fma_f32 v54, v48, s30, -v51
	v_rcp_f32_e32 v51, v49
	v_fmac_f32_e32 v54, 0x3377d1cf, v48
	v_fmac_f32_e32 v54, 0x3f317217, v48
	v_cmp_lt_f32_e64 s[4:5], |v48|, s31
	v_fma_f32 v49, v32, v51, v57
	v_exp_f32_e32 v50, v50
	v_cndmask_b32_e64 v48, v48, v54, s[4:5]
	v_cmp_gt_f32_e64 s[4:5], s29, v49
	s_waitcnt lgkmcnt(5)
	v_lshlrev_b32_e32 v52, 16, v52
	v_mul_f32_e32 v52, 0xbfb8aa3b, v52
	v_cndmask_b32_e64 v54, 0, 32, s[4:5]
	v_ldexp_f32 v49, v49, v54
	v_log_f32_e32 v49, v49
	v_cndmask_b32_e32 v54, 0, v64, vcc
	v_sub_f32_e32 v82, v48, v54
	v_exp_f32_e32 v52, v52
	v_mul_f32_e32 v48, 0x3f317217, v49
	v_fma_f32 v48, v49, s30, -v48
	v_fmac_f32_e32 v48, 0x3377d1cf, v49
	v_fmac_f32_e32 v48, 0x3f317217, v49
	v_cmp_lt_f32_e64 vcc, |v49|, s31
	v_add_f32_e32 v52, 1.0, v52
	v_rcp_f32_e32 v55, v52
	v_cndmask_b32_e32 v48, v49, v48, vcc
	v_cndmask_b32_e64 v49, 0, v64, s[4:5]
	v_sub_f32_e32 v84, v48, v49
	v_add_f32_e32 v48, 1.0, v50
	v_rcp_f32_e32 v50, v48
	ds_read_u16 v48, v68 offset:2176
	ds_read_u16 v49, v68 offset:2448
	ds_read_u16 v85, v68 offset:2720
	ds_read_u16 v86, v68 offset:2992
	ds_read_u16 v87, v68 offset:3264
	ds_read_u16 v88, v68 offset:3536
	ds_read_u16 v89, v68 offset:3808
	ds_read_u16 v90, v68 offset:4080
	s_waitcnt lgkmcnt(7)
	v_lshlrev_b32_e32 v91, 16, v48
	v_fma_f32 v52, v32, v55, v57
	v_fma_f32 v48, v32, v50, v57
	v_cmp_gt_f32_e32 vcc, s29, v48
	s_waitcnt lgkmcnt(6)
; __device__ __forceinline__ float bf2f(unsigned h) { return __uint_as_float(h << 16); }
; __device__ __forceinline__ float sigmf(float x) { return __builtin_amdgcn_rcpf(1.0f + __expf(-x)); }
; __device__ __forceinline__ void hg_a_unit(const Params& p, LAS unsigned char* lds, int unit, int next_unit, u32x4 (&pre)[6]) {
;     ...
;         for (int i = 0; i < 16; ++i) { const int t = sub * 16 + i; const float f = bf2f(KI[t * 136 + d]); const float sg = sigmf(f);
;             run += __logf(lb + omlb * sg); cl[i] = run; kq[i] = omlb * (1.0f - sg); q[i] = bf2f(QD[t * 136 + d]); vv[i] = VR[t * 136 + d]; }
;         ST[sub * 128 + d] = run;
;         __syncthreads();
	v_lshlrev_b32_e32 v93, 16, v49
	v_lshlrev_b32_e32 v49, 16, v53
	v_cndmask_b32_e64 v54, 0, 32, vcc
	v_ldexp_f32 v48, v48, v54
	v_log_f32_e32 v48, v48
	v_mul_f32_e32 v49, 0xbfb8aa3b, v49
	v_exp_f32_e32 v49, v49
	ds_read_u16 v105, v68 offset:34816
	ds_read_u16 v106, v68 offset:35360
	ds_read_u16 v107, v68 offset:35904
	ds_read_u16 v108, v68 offset:36448
	ds_read_u16 v109, v68 offset:36720
	ds_read_u16 v110, v68 offset:36176
	ds_read_u16 v111, v68 offset:35632
	ds_read_u16 v112, v68 offset:35088
	ds_read_u16 v113, v68 offset:36992
	ds_read_u16 v114, v68 offset:37536
	ds_read_u16 v115, v68 offset:38080
	ds_read_u16 v116, v68 offset:38624
	ds_read_u16 v117, v68 offset:38896
	ds_read_u16 v118, v68 offset:38352
	ds_read_u16 v119, v68 offset:37808
	ds_read_u16 v120, v68 offset:37264
	v_mul_f32_e32 v54, 0x3f317217, v48
	v_fma_f32 v54, v48, s30, -v54
	v_fmac_f32_e32 v54, 0x3377d1cf, v48
	v_fmac_f32_e32 v54, 0x3f317217, v48
	v_cmp_lt_f32_e64 s[4:5], |v48|, s31
	v_add_f32_e32 v49, 1.0, v49
	v_pk_mul_f32 v[46:47], v[32:33], v[46:47] op_sel_hi:[0,1]
	v_cndmask_b32_e64 v48, v48, v54, s[4:5]
	v_cmp_gt_f32_e64 s[4:5], s29, v52
	v_pk_add_f32 v[50:51], v[50:51], 1.0 op_sel_hi:[1,0] neg_lo:[1,0] neg_hi:[1,0]
	s_waitcnt lgkmcnt(14)
	v_lshlrev_b32_e32 v85, 16, v85
	v_cndmask_b32_e64 v54, 0, 32, s[4:5]
	v_ldexp_f32 v52, v52, v54
	v_log_f32_e32 v52, v52
	v_cndmask_b32_e32 v54, 0, v64, vcc
	v_sub_f32_e32 v92, v48, v54
	v_rcp_f32_e32 v54, v49
	v_mul_f32_e32 v48, 0x3f317217, v52
	v_fma_f32 v48, v52, s30, -v48
	v_fmac_f32_e32 v48, 0x3377d1cf, v52
	v_fmac_f32_e32 v48, 0x3f317217, v52
	v_cmp_lt_f32_e64 vcc, |v52|, s31
	v_cndmask_b32_e64 v49, 0, v64, s[4:5]
	v_pk_mul_f32 v[50:51], v[32:33], v[50:51] op_sel_hi:[0,1]
	v_cndmask_b32_e32 v48, v52, v48, vcc
	v_sub_f32_e32 v94, v48, v49
	v_fma_f32 v48, v32, v54, v57
	v_cmp_gt_f32_e32 vcc, s29, v48
	v_lshlrev_b32_e32 v86, 16, v86
	v_pk_add_f32 v[54:55], v[54:55], 1.0 op_sel_hi:[1,0] neg_lo:[1,0] neg_hi:[1,0]
	v_cndmask_b32_e64 v49, 0, 32, vcc
	v_ldexp_f32 v48, v48, v49
	v_lshlrev_b32_e32 v49, 16, v75
	v_mul_f32_e32 v49, 0xbfb8aa3b, v49
	v_exp_f32_e32 v49, v49
	v_log_f32_e32 v48, v48
	v_pk_mul_f32 v[54:55], v[32:33], v[54:55] op_sel_hi:[0,1]
	v_lshlrev_b32_e32 v87, 16, v87
	v_add_f32_e32 v49, 1.0, v49
	v_rcp_f32_e32 v53, v49
	v_mul_f32_e32 v52, 0x3f317217, v48
	v_fma_f32 v52, v48, s30, -v52
	v_fmac_f32_e32 v52, 0x3377d1cf, v48
	v_fmac_f32_e32 v52, 0x3f317217, v48
	v_cmp_lt_f32_e64 s[4:5], |v48|, s31
	v_fma_f32 v49, v32, v53, v57
	v_lshlrev_b32_e32 v88, 16, v88
	v_cndmask_b32_e64 v48, v48, v52, s[4:5]
	v_cmp_gt_f32_e64 s[4:5], s29, v49
	v_lshlrev_b32_e32 v89, 16, v89
	v_lshlrev_b32_e32 v90, 16, v90
	v_cndmask_b32_e64 v52, 0, 32, s[4:5]
	v_ldexp_f32 v49, v49, v52
	v_cndmask_b32_e32 v52, 0, v64, vcc
	v_sub_f32_e32 v95, v48, v52
	v_lshlrev_b32_e32 v52, 16, v79
	v_mul_f32_e32 v52, 0xbfb8aa3b, v52
	v_log_f32_e32 v49, v49
	v_exp_f32_e32 v52, v52
	v_mul_f32_e32 v48, 0x3f317217, v49
	v_add_f32_e32 v52, 1.0, v52
	v_fma_f32 v48, v49, s30, -v48
	v_rcp_f32_e32 v52, v52
	v_fmac_f32_e32 v48, 0x3377d1cf, v49
	v_fmac_f32_e32 v48, 0x3f317217, v49
	v_cmp_lt_f32_e64 vcc, |v49|, s31
	s_nop 1
	v_cndmask_b32_e32 v48, v49, v48, vcc
	v_cndmask_b32_e64 v49, 0, v64, s[4:5]
	v_sub_f32_e32 v79, v48, v49
	v_fma_f32 v48, v32, v52, v57
	v_cmp_gt_f32_e32 vcc, s29, v48
	v_pk_add_f32 v[52:53], v[52:53], 1.0 op_sel_hi:[1,0] neg_lo:[1,0] neg_hi:[1,0]
	s_nop 0
	v_cndmask_b32_e64 v49, 0, 32, vcc
	v_ldexp_f32 v48, v48, v49
	v_lshlrev_b32_e32 v49, 16, v80
	v_mul_f32_e32 v49, 0xbfb8aa3b, v49
	v_exp_f32_e32 v49, v49
	v_log_f32_e32 v48, v48
	v_pk_mul_f32 v[52:53], v[32:33], v[52:53] op_sel_hi:[0,1]
	v_add_f32_e32 v49, 1.0, v49
	v_mul_f32_e32 v75, 0x3f317217, v48
	v_rcp_f32_e32 v49, v49
	v_fma_f32 v75, v48, s30, -v75
	v_fmac_f32_e32 v75, 0x3377d1cf, v48
	v_fmac_f32_e32 v75, 0x3f317217, v48
	v_cmp_lt_f32_e64 s[4:5], |v48|, s31
	s_nop 1
	v_cndmask_b32_e64 v48, v48, v75, s[4:5]
	v_fma_f32 v75, v32, v49, v57
	v_cmp_gt_f32_e64 s[4:5], s29, v75
	s_nop 1
	v_cndmask_b32_e64 v80, 0, 32, s[4:5]
	v_ldexp_f32 v75, v75, v80
	v_lshlrev_b32_e32 v80, 16, v81
	v_mul_f32_e32 v80, 0xbfb8aa3b, v80
	v_exp_f32_e32 v80, v80
	v_cndmask_b32_e32 v81, 0, v64, vcc
	v_sub_f32_e32 v81, v48, v81
	v_log_f32_e32 v75, v75
	v_add_f32_e32 v48, 1.0, v80
	v_rcp_f32_e32 v48, v48
	v_mul_f32_e32 v96, 0x3f317217, v75
	v_fma_f32 v80, v75, s30, -v96
	v_fmac_f32_e32 v57, v32, v48
	v_cmp_gt_f32_e32 vcc, s29, v57
	v_fmac_f32_e32 v80, 0x3377d1cf, v75
	v_fmac_f32_e32 v80, 0x3f317217, v75
	v_cndmask_b32_e64 v96, 0, 32, vcc
	v_ldexp_f32 v57, v57, v96
	v_log_f32_e32 v57, v57
	v_cmp_lt_f32_e64 s[6:7], |v75|, s31
	v_lshl_add_u32 v96, v66, 2, s33
	v_pk_add_f32 v[48:49], v[48:49], 1.0 op_sel_hi:[1,0] neg_lo:[1,0] neg_hi:[1,0]
	v_cndmask_b32_e64 v75, v75, v80, s[6:7]
	v_cndmask_b32_e64 v80, 0, v64, s[4:5]
	v_sub_f32_e32 v80, v75, v80
	v_mul_f32_e32 v75, 0x3f317217, v57
	v_fma_f32 v75, v57, s30, -v75
	v_fmac_f32_e32 v75, 0x3377d1cf, v57
	v_fmac_f32_e32 v75, 0x3f317217, v57
	v_cmp_lt_f32_e64 s[4:5], |v57|, s31
	v_pk_mul_f32 v[48:49], v[32:33], v[48:49] op_sel_hi:[0,1]
	s_or_b32 s6, s17, s16
	v_cndmask_b32_e64 v57, v57, v75, s[4:5]
	v_cndmask_b32_e32 v75, 0, v64, vcc
	v_sub_f32_e32 v57, v57, v75
	v_add_f32_e32 v75, v28, v58
	v_add_f32_e32 v98, v75, v59
	v_add_f32_e32 v99, v98, v74
	v_add_f32_e32 v100, v99, v76
	v_add_f32_e32 v101, v100, v77
	v_add_f32_e32 v102, v101, v78
	v_add_f32_e32 v82, v102, v82
	v_add_f32_e32 v84, v82, v84
	v_add_f32_e32 v92, v84, v92
	v_add_f32_e32 v94, v92, v94
	v_add_f32_e32 v95, v94, v95
	v_add_f32_e32 v103, v95, v79
	v_add_f32_e32 v81, v103, v81
	v_add_f32_e32 v80, v81, v80
	v_add_f32_e32 v104, v80, v57
	ds_write_b32 v96, v104
	s_waitcnt lgkmcnt(0)
	s_barrier
; __device__ __forceinline__ unsigned f2bf(float f) { unsigned u = __float_as_uint(f); return (u + 0x7fffu + ((u >> 16) & 1u)) >> 16; }
; __device__ __forceinline__ void hg_a_unit(const Params& p, LAS unsigned char* lds, int unit, int next_unit, u32x4 (&pre)[6]) {
;     ...
;         float off = 0.f, total = 0.f;
; #pragma unroll
;         for (int s = 0; s < 4; ++s) { const float x = ST[s * 128 + d]; total += x; if (s < sub) off += x; }
;         unsigned ke[8], vp[8];
; #pragma unroll
;         for (int i = 0; i < 16; ++i) { const float cum = off + cl[i]; const unsigned qd = f2bf(q[i] * __expf(cum)), ki = f2bf(kq[i] * __expf(-cum)), kE = f2bf(kq[i] * __expf(total - cum));
;             QD[(sub * 16 + i) * 136 + d] = (bf16_t)qd; KI[(sub * 16 + i) * 136 + d] = (bf16_t)ki;
;             if (i & 1) { ke[i >> 1] |= kE << 16; vp[i >> 1] |= (unsigned)vv[i] << 16; } else { ke[i >> 1] = kE; vp[i >> 1] = vv[i]; } }
	ds_read2st64_b32 v[76:77], v97 offset1:2
	ds_read2st64_b32 v[78:79], v97 offset0:4 offset1:6
	v_cmp_lt_i32_e32 vcc, 0, v45
	s_waitcnt lgkmcnt(1)
	v_add_f32_e32 v57, 0, v76
	v_cndmask_b32_e32 v58, 0, v57, vcc
	v_add_f32_e32 v59, v77, v58
	v_cmp_lt_i32_e32 vcc, 1, v45
	v_add_f32_e32 v57, v57, v77
	s_waitcnt lgkmcnt(0)
	v_add_f32_e32 v74, v57, v78
	v_cndmask_b32_e32 v58, v58, v59, vcc
	v_add_f32_e32 v59, v78, v58
	v_cmp_lt_i32_e32 vcc, 2, v45
	s_nop 1
	v_cndmask_b32_e32 v58, v58, v59, vcc
	v_add_f32_e32 v59, v79, v58
	v_cmp_lt_i32_e32 vcc, 3, v45
	s_nop 1
	v_cndmask_b32_e32 v59, v58, v59, vcc
	v_add_f32_e32 v28, v28, v59
	v_mul_f32_e32 v58, 0x3fb8aa3b, v28
	v_exp_f32_e32 v58, v58
	s_nop 0
	v_mul_f32_e32 v56, v58, v56
	v_bfe_u32 v57, v56, 16, 1
	v_add3_u32 v56, v56, v57, s34
	v_mul_f32_e32 v57, 0xbfb8aa3b, v28
	v_mov_b32_e32 v58, v79
	v_exp_f32_e32 v76, v57
	ds_write_b16_d16_hi v68, v56
	v_pk_add_f32 v[56:57], v[74:75], v[58:59]
	s_nop 0
	v_mul_f32_e32 v58, 0x3fb8aa3b, v57
	v_exp_f32_e32 v58, v58
	v_sub_f32_e32 v28, v56, v28
	v_mul_f32_e32 v28, 0x3fb8aa3b, v28
	v_exp_f32_e32 v75, v28
	v_mul_f32_e32 v28, v58, v73
	v_bfe_u32 v58, v28, 16, 1
	v_add3_u32 v28, v28, v58, s34
	v_mul_f32_e32 v58, 0xbfb8aa3b, v57
	ds_write_b16_d16_hi v68, v28 offset:272
	v_sub_f32_e32 v28, v56, v57
	v_exp_f32_e32 v58, v58
	v_mul_f32_e32 v28, 0x3fb8aa3b, v28
	v_exp_f32_e32 v74, v28
	v_mul_f32_e32 v28, v25, v76
	v_bfe_u32 v57, v28, 16, 1
	v_add3_u32 v28, v28, v57, s34
	ds_write_b16_d16_hi v68, v28 offset:17408
	v_mul_f32_e32 v28, v24, v58
	v_bfe_u32 v57, v28, 16, 1
	v_pk_mul_f32 v[24:25], v[24:25], v[74:75]
	v_add3_u32 v28, v28, v57, s34
	v_and_b32_sdwa v57, v24, v65 dst_sel:DWORD dst_unused:UNUSED_PAD src0_sel:WORD_1 src1_sel:DWORD
	ds_write_b16_d16_hi v68, v28 offset:17680
	v_and_b32_sdwa v28, v25, v65 dst_sel:DWORD dst_unused:UNUSED_PAD src0_sel:WORD_1 src1_sel:DWORD
	v_add3_u32 v24, v24, v57, s34
	v_add_f32_e32 v57, v98, v59
	v_add3_u32 v25, v25, v28, s34
	v_mul_f32_e32 v28, 0x3fb8aa3b, v57
	v_exp_f32_e32 v58, v28
	v_lshrrev_b32_e32 v25, 16, v25
	v_and_or_b32 v28, v24, s35, v25
	v_lshl_or_b32 v24, v112, 16, v105
	v_mul_f32_e32 v25, v58, v29
	v_bfe_u32 v29, v25, 16, 1
	v_add3_u32 v25, v25, v29, s34
	ds_write_b16_d16_hi v68, v25 offset:544
	v_add_f32_e32 v25, v99, v59
	v_mul_f32_e32 v58, 0x3fb8aa3b, v25
	v_exp_f32_e32 v58, v58
	v_mul_f32_e32 v29, 0xbfb8aa3b, v57
	v_sub_f32_e32 v57, v56, v57
	v_mul_f32_e32 v57, 0x3fb8aa3b, v57
	v_exp_f32_e32 v29, v29
	v_exp_f32_e32 v73, v57
	v_mul_f32_e32 v57, v58, v72
	v_bfe_u32 v58, v57, 16, 1
	v_add3_u32 v57, v57, v58, s34
	v_mul_f32_e32 v58, 0xbfb8aa3b, v25
	v_sub_f32_e32 v25, v56, v25
	v_exp_f32_e32 v58, v58
	v_mul_f32_e32 v25, 0x3fb8aa3b, v25
	v_exp_f32_e32 v72, v25
	v_mul_f32_e32 v25, v31, v29
	v_bfe_u32 v29, v25, 16, 1
	v_add3_u32 v25, v25, v29, s34
	ds_write_b16_d16_hi v68, v25 offset:17952
	v_mul_f32_e32 v25, v30, v58
	v_bfe_u32 v29, v25, 16, 1
	v_pk_mul_f32 v[30:31], v[30:31], v[72:73]
	v_add3_u32 v25, v25, v29, s34
	v_and_b32_sdwa v29, v30, v65 dst_sel:DWORD dst_unused:UNUSED_PAD src0_sel:WORD_1 src1_sel:DWORD
	ds_write_b16_d16_hi v68, v25 offset:18224
	v_and_b32_sdwa v25, v31, v65 dst_sel:DWORD dst_unused:UNUSED_PAD src0_sel:WORD_1 src1_sel:DWORD
	v_add3_u32 v29, v30, v29, s34
	v_add_f32_e32 v30, v100, v59
	v_add3_u32 v25, v31, v25, s34
	v_mul_f32_e32 v31, 0x3fb8aa3b, v30
	v_exp_f32_e32 v31, v31
	ds_write_b16_d16_hi v68, v57 offset:816
	v_add_f32_e32 v58, v101, v59
	v_lshrrev_b32_e32 v25, 16, v25
	v_mul_f32_e32 v31, v31, v70
	v_bfe_u32 v57, v31, 16, 1
	v_add3_u32 v31, v31, v57, s34
	ds_write_b16_d16_hi v68, v31 offset:1088
	v_mul_f32_e32 v31, 0x3fb8aa3b, v58
	v_exp_f32_e32 v70, v31
	v_mul_f32_e32 v57, 0xbfb8aa3b, v30
	v_sub_f32_e32 v30, v56, v30
	v_mul_f32_e32 v30, 0x3fb8aa3b, v30
	v_exp_f32_e32 v31, v30
	v_mul_f32_e32 v30, v70, v71
	v_bfe_u32 v70, v30, 16, 1
	v_exp_f32_e32 v57, v57
	v_add3_u32 v30, v30, v70, s34
	ds_write_b16_d16_hi v68, v30 offset:1360
	v_sub_f32_e32 v30, v56, v58
	v_mul_f32_e32 v70, 0xbfb8aa3b, v58
	v_mul_f32_e32 v30, 0x3fb8aa3b, v30
	v_exp_f32_e32 v70, v70
	v_exp_f32_e32 v30, v30
	v_mul_f32_e32 v57, v27, v57
	v_bfe_u32 v58, v57, 16, 1
	v_add3_u32 v57, v57, v58, s34
	ds_write_b16_d16_hi v68, v57 offset:18496
	v_mul_f32_e32 v57, v26, v70
	v_pk_mul_f32 v[26:27], v[26:27], v[30:31]
	v_bfe_u32 v58, v57, 16, 1
	v_and_b32_sdwa v31, v26, v65 dst_sel:DWORD dst_unused:UNUSED_PAD src0_sel:WORD_1 src1_sel:DWORD
	v_and_b32_sdwa v30, v27, v65 dst_sel:DWORD dst_unused:UNUSED_PAD src0_sel:WORD_1 src1_sel:DWORD
	v_add3_u32 v26, v26, v31, s34
	v_add_f32_e32 v31, v102, v59
	v_add3_u32 v57, v57, v58, s34
	v_add3_u32 v27, v27, v30, s34
	v_mul_f32_e32 v30, 0x3fb8aa3b, v31
	ds_write_b16_d16_hi v68, v57 offset:18768
	v_exp_f32_e32 v57, v30
	v_lshrrev_b32_e32 v27, 16, v27
	v_and_or_b32 v30, v26, s35, v27
	v_and_or_b32 v29, v29, s35, v25
	v_mul_f32_e32 v27, v57, v69
	v_bfe_u32 v57, v27, 16, 1
	v_add3_u32 v27, v27, v57, s34
	ds_write_b16_d16_hi v68, v27 offset:1632
	v_add_f32_e32 v27, v82, v59
	v_mul_f32_e32 v58, 0x3fb8aa3b, v27
	v_exp_f32_e32 v58, v58
	v_mul_f32_e32 v57, 0xbfb8aa3b, v31
	v_sub_f32_e32 v31, v56, v31
	v_mul_f32_e32 v31, 0x3fb8aa3b, v31
	v_exp_f32_e32 v57, v57
	v_exp_f32_e32 v71, v31
	v_mul_f32_e32 v31, v58, v83
	v_bfe_u32 v58, v31, 16, 1
	v_add3_u32 v31, v31, v58, s34
	v_mul_f32_e32 v58, 0xbfb8aa3b, v27
	v_sub_f32_e32 v27, v56, v27
	v_exp_f32_e32 v58, v58
	v_mul_f32_e32 v27, 0x3fb8aa3b, v27
	v_exp_f32_e32 v70, v27
	v_mul_f32_e32 v27, v47, v57
	ds_write_b16_d16_hi v68, v31 offset:1904
	v_bfe_u32 v31, v27, 16, 1
	v_add3_u32 v27, v27, v31, s34
	ds_write_b16_d16_hi v68, v27 offset:19040
	v_mul_f32_e32 v27, v46, v58
; __device__ __forceinline__ unsigned f2bf(float f) { unsigned u = __float_as_uint(f); return (u + 0x7fffu + ((u >> 16) & 1u)) >> 16; }
; __device__ __forceinline__ void hg_a_unit(const Params& p, LAS unsigned char* lds, int unit, int next_unit, u32x4 (&pre)[6]) {
;     ...
;         for (int i = 0; i < 16; ++i) { const float cum = off + cl[i]; const unsigned qd = f2bf(q[i] * __expf(cum)), ki = f2bf(kq[i] * __expf(-cum)), kE = f2bf(kq[i] * __expf(total - cum));
;             QD[(sub * 16 + i) * 136 + d] = (bf16_t)qd; KI[(sub * 16 + i) * 136 + d] = (bf16_t)ki;
;             if (i & 1) { ke[i >> 1] |= kE << 16; vp[i >> 1] |= (unsigned)vv[i] << 16; } else { ke[i >> 1] = kE; vp[i >> 1] = vv[i]; } }
	v_bfe_u32 v31, v27, 16, 1
	v_pk_mul_f32 v[46:47], v[46:47], v[70:71]
	v_add3_u32 v27, v27, v31, s34
	v_and_b32_sdwa v31, v46, v65 dst_sel:DWORD dst_unused:UNUSED_PAD src0_sel:WORD_1 src1_sel:DWORD
	ds_write_b16_d16_hi v68, v27 offset:19312
	v_and_b32_sdwa v27, v47, v65 dst_sel:DWORD dst_unused:UNUSED_PAD src0_sel:WORD_1 src1_sel:DWORD
	v_add3_u32 v31, v46, v31, s34
	v_add_f32_e32 v46, v84, v59
	v_add3_u32 v27, v47, v27, s34
	v_mul_f32_e32 v47, 0x3fb8aa3b, v46
	v_exp_f32_e32 v47, v47
	v_add_f32_e32 v58, v92, v59
	v_lshrrev_b32_e32 v27, 16, v27
	v_lshl_or_b32 v25, v111, 16, v106
	v_mul_f32_e32 v47, v47, v91
	v_bfe_u32 v57, v47, 16, 1
	v_add3_u32 v47, v47, v57, s34
	ds_write_b16_d16_hi v68, v47 offset:2176
	v_mul_f32_e32 v47, 0x3fb8aa3b, v58
	v_exp_f32_e32 v69, v47
	v_mul_f32_e32 v57, 0xbfb8aa3b, v46
	v_sub_f32_e32 v46, v56, v46
	v_mul_f32_e32 v46, 0x3fb8aa3b, v46
	v_exp_f32_e32 v47, v46
	v_mul_f32_e32 v46, v69, v93
	v_bfe_u32 v69, v46, 16, 1
	v_add3_u32 v46, v46, v69, s34
	v_exp_f32_e32 v57, v57
	ds_write_b16_d16_hi v68, v46 offset:2448
	v_sub_f32_e32 v46, v56, v58
	v_mul_f32_e32 v46, 0x3fb8aa3b, v46
	v_mul_f32_e32 v69, 0xbfb8aa3b, v58
	v_exp_f32_e32 v46, v46
	v_exp_f32_e32 v69, v69
	v_mul_f32_e32 v57, v51, v57
	v_bfe_u32 v58, v57, 16, 1
	v_add3_u32 v57, v57, v58, s34
	v_pk_mul_f32 v[46:47], v[50:51], v[46:47]
	ds_write_b16_d16_hi v68, v57 offset:19584
	v_mul_f32_e32 v57, v50, v69
	v_and_b32_sdwa v51, v46, v65 dst_sel:DWORD dst_unused:UNUSED_PAD src0_sel:WORD_1 src1_sel:DWORD
	v_bfe_u32 v58, v57, 16, 1
	v_and_b32_sdwa v50, v47, v65 dst_sel:DWORD dst_unused:UNUSED_PAD src0_sel:WORD_1 src1_sel:DWORD
	v_add3_u32 v46, v46, v51, s34
	v_add_f32_e32 v51, v94, v59
	v_add3_u32 v57, v57, v58, s34
	v_add3_u32 v47, v47, v50, s34
	v_mul_f32_e32 v50, 0x3fb8aa3b, v51
	ds_write_b16_d16_hi v68, v57 offset:19856
	v_exp_f32_e32 v57, v50
	v_lshrrev_b32_e32 v47, 16, v47
	v_and_or_b32 v50, v46, s35, v47
	v_lshl_or_b32 v26, v110, 16, v107
	v_mul_f32_e32 v46, v57, v85
	v_bfe_u32 v47, v46, 16, 1
	v_add3_u32 v46, v46, v47, s34
	v_mul_f32_e32 v47, 0xbfb8aa3b, v51
	ds_write_b16_d16_hi v68, v46 offset:2720
	v_add_f32_e32 v46, v95, v59
	v_exp_f32_e32 v57, v47
	v_mul_f32_e32 v47, 0x3fb8aa3b, v46
	v_exp_f32_e32 v58, v47
	v_sub_f32_e32 v47, v56, v51
	v_mul_f32_e32 v47, 0x3fb8aa3b, v47
	v_exp_f32_e32 v47, v47
	v_mul_f32_e32 v51, v58, v86
	v_bfe_u32 v58, v51, 16, 1
	v_add3_u32 v51, v51, v58, s34
	v_mul_f32_e32 v58, 0xbfb8aa3b, v46
	v_sub_f32_e32 v46, v56, v46
	v_exp_f32_e32 v58, v58
	v_mul_f32_e32 v46, 0x3fb8aa3b, v46
	ds_write_b16_d16_hi v68, v51 offset:2992
	v_exp_f32_e32 v46, v46
	v_mul_f32_e32 v51, v55, v57
	v_bfe_u32 v57, v51, 16, 1
	v_add3_u32 v51, v51, v57, s34
	ds_write_b16_d16_hi v68, v51 offset:20128
	v_mul_f32_e32 v51, v54, v58
	v_bfe_u32 v57, v51, 16, 1
	v_pk_mul_f32 v[46:47], v[54:55], v[46:47]
	v_add3_u32 v51, v51, v57, s34
	v_and_b32_sdwa v54, v46, v65 dst_sel:DWORD dst_unused:UNUSED_PAD src0_sel:WORD_1 src1_sel:DWORD
	ds_write_b16_d16_hi v68, v51 offset:20400
	v_and_b32_sdwa v51, v47, v65 dst_sel:DWORD dst_unused:UNUSED_PAD src0_sel:WORD_1 src1_sel:DWORD
	v_add3_u32 v46, v46, v54, s34
	v_add_f32_e32 v54, v103, v59
	v_add3_u32 v47, v47, v51, s34
	v_mul_f32_e32 v51, 0x3fb8aa3b, v54
	v_exp_f32_e32 v55, v51
	v_lshrrev_b32_e32 v47, 16, v47
	v_and_or_b32 v51, v46, s35, v47
	v_and_or_b32 v31, v31, s35, v27
	v_mul_f32_e32 v46, v55, v87
	v_bfe_u32 v47, v46, 16, 1
	v_add3_u32 v46, v46, v47, s34
	v_mul_f32_e32 v47, 0xbfb8aa3b, v54
	ds_write_b16_d16_hi v68, v46 offset:3264
	v_add_f32_e32 v46, v81, v59
	v_exp_f32_e32 v55, v47
	v_mul_f32_e32 v47, 0x3fb8aa3b, v46
	v_exp_f32_e32 v57, v47
	v_sub_f32_e32 v47, v56, v54
	v_mul_f32_e32 v47, 0x3fb8aa3b, v47
	v_exp_f32_e32 v47, v47
	v_mul_f32_e32 v54, v57, v88
	v_bfe_u32 v57, v54, 16, 1
	v_add3_u32 v54, v54, v57, s34
	v_mul_f32_e32 v57, 0xbfb8aa3b, v46
	v_sub_f32_e32 v46, v56, v46
	v_mul_f32_e32 v46, 0x3fb8aa3b, v46
	v_exp_f32_e32 v46, v46
	v_exp_f32_e32 v57, v57
	ds_write_b16_d16_hi v68, v54 offset:3536
	v_mul_f32_e32 v54, v53, v55
	v_bfe_u32 v55, v54, 16, 1
	v_add3_u32 v54, v54, v55, s34
	v_pk_mul_f32 v[46:47], v[52:53], v[46:47]
	ds_write_b16_d16_hi v68, v54 offset:20672
	v_mul_f32_e32 v54, v52, v57
	v_and_b32_sdwa v53, v46, v65 dst_sel:DWORD dst_unused:UNUSED_PAD src0_sel:WORD_1 src1_sel:DWORD
	v_bfe_u32 v55, v54, 16, 1
	v_and_b32_sdwa v52, v47, v65 dst_sel:DWORD dst_unused:UNUSED_PAD src0_sel:WORD_1 src1_sel:DWORD
	v_add3_u32 v46, v46, v53, s34
	v_add_f32_e32 v53, v80, v59
	v_add3_u32 v54, v54, v55, s34
	v_add3_u32 v47, v47, v52, s34
	v_mul_f32_e32 v52, 0x3fb8aa3b, v53
	ds_write_b16_d16_hi v68, v54 offset:20944
	v_exp_f32_e32 v54, v52
	v_lshrrev_b32_e32 v47, 16, v47
	v_and_or_b32 v52, v46, s35, v47
	v_lshl_or_b32 v27, v109, 16, v108
	v_mul_f32_e32 v46, v54, v89
	v_bfe_u32 v47, v46, 16, 1
	v_add3_u32 v46, v46, v47, s34
	v_mul_f32_e32 v47, 0xbfb8aa3b, v53
	ds_write_b16_d16_hi v68, v46 offset:3808
; #define LAS __attribute__((address_space(3)))
; __device__ __forceinline__ void hg_a_prefetch(const bf16_t* Z, int unit, int tid, u32x4 (&pre)[6]) {
;     const int b = unit >> 9, h = (unit >> 6) & 7, n = unit & 63; const int tok0 = b * SEQ + n * 64;
; #pragma unroll
;     for (int q = 0; q < 6; ++q) { const int i = tid + q * NT; const int arr = i >> 10, row = (i >> 4) & 63, cc = i & 15; pre[q] = __builtin_nontemporal_load((const u32x4*)(Z + (size_t)(tok0 + row) * ZW + 2048 + 1024 * arr + h * 128 + 8 * cc)); }
; __device__ __forceinline__ void hg_a_unit(const Params& p, LAS unsigned char* lds, int unit, int next_unit, u32x4 (&pre)[6]) {
;     ...
;         *(LAS u32x4*)(VT + d * 72 + sub * 16) = (u32x4){vp[0], vp[1], vp[2], vp[3]}; *(LAS u32x4*)(VT + d * 72 + sub * 16 + 8) = (u32x4){vp[4], vp[5], vp[6], vp[7]};
;         bf16_t* tb = Z + (size_t)(tok0 + (d >> 1)) * ZW + h * 128 + (d & 1) * 64 + sub * 16;
;         *(u32x4*)(tb + 3072) = (u32x4){ke[0], ke[1], ke[2], ke[3]}; *(u32x4*)(tb + 3072 + 8) = (u32x4){ke[4], ke[5], ke[6], ke[7]};
;         *(u32x4*)(tb + 4096) = (u32x4){vp[0], vp[1], vp[2], vp[3]}; *(u32x4*)(tb + 4096 + 8) = (u32x4){vp[4], vp[5], vp[6], vp[7]};
;         if (sub == 0) ((float*)(WSP + WS_DEC))[unit * 128 + d] = __expf(total);
;     }
;     __syncthreads();
;     if (next_unit < 2048) hg_a_prefetch(Z, next_unit, tid, pre);
	v_add_f32_e32 v46, v104, v59
	v_exp_f32_e32 v54, v47
	v_mul_f32_e32 v47, 0x3fb8aa3b, v46
	v_exp_f32_e32 v55, v47
	v_sub_f32_e32 v47, v56, v53
	v_mul_f32_e32 v47, 0x3fb8aa3b, v47
	v_mul_f32_e32 v32, v49, v54
	v_mul_f32_e32 v53, v55, v90
	v_bfe_u32 v55, v53, 16, 1
	v_add3_u32 v53, v53, v55, s34
	v_mul_f32_e32 v55, 0xbfb8aa3b, v46
	v_exp_f32_e32 v55, v55
	v_sub_f32_e32 v46, v56, v46
	v_mul_f32_e32 v46, 0x3fb8aa3b, v46
	v_exp_f32_e32 v47, v47
	ds_write_b16_d16_hi v68, v53 offset:4080
	v_exp_f32_e32 v46, v46
	v_bfe_u32 v53, v32, 16, 1
	v_add3_u32 v32, v32, v53, s34
	ds_write_b16_d16_hi v68, v32 offset:21216
	v_mul_f32_e32 v32, v48, v55
	v_bfe_u32 v53, v32, 16, 1
	v_add3_u32 v32, v32, v53, s34
	v_pk_mul_f32 v[46:47], v[48:49], v[46:47]
	ds_write_b16_d16_hi v68, v32 offset:21488
	v_and_b32_sdwa v32, v47, v65 dst_sel:DWORD dst_unused:UNUSED_PAD src0_sel:WORD_1 src1_sel:DWORD
	v_and_b32_sdwa v48, v46, v65 dst_sel:DWORD dst_unused:UNUSED_PAD src0_sel:WORD_1 src1_sel:DWORD
	v_add3_u32 v32, v47, v32, s34
	v_add3_u32 v46, v46, v48, s34
	v_lshrrev_b32_e32 v32, 16, v32
	v_and_or_b32 v53, v46, s35, v32
	v_mul_u32_u24_e32 v32, 0x90, v39
	v_lshlrev_b32_e32 v39, 5, v45
	v_add3_u32 v32, 0, v32, v39
	v_lshl_or_b32 v70, v120, 16, v113
	v_lshl_or_b32 v71, v119, 16, v114
	v_lshl_or_b32 v72, v118, 16, v115
	v_lshl_or_b32 v73, v117, 16, v116
	ds_write_b128 v32, v[24:27] offset:52224
	ds_write_b128 v32, v[70:73] offset:52240
	v_bfe_u32 v32, v66, 1, 6
	v_or_b32_e32 v32, s6, v32
	v_mov_b64_e32 v[46:47], s[14:15]
	v_mad_i64_i32 v[46:47], s[4:5], v32, s3, v[46:47]
	v_lshlrev_b32_e32 v32, 7, v66
	v_lshl_add_u64 v[46:47], v[46:47], 0, s[8:9]
	v_and_b32_e32 v32, 0x80, v32
	v_lshl_add_u64 v[46:47], v[46:47], 0, v[32:33]
	v_ashrrev_i32_e32 v45, 31, v44
	v_lshl_add_u64 v[44:45], v[44:45], 1, v[46:47]
	v_add_co_u32_e32 v46, vcc, 0x1000, v44
	s_nop 1
	v_addc_co_u32_e32 v47, vcc, 0, v45, vcc
	global_store_dwordx4 v[46:47], v[28:31], off offset:2048
	global_store_dwordx4 v[46:47], v[50:53], off offset:2064
	s_nop 0
	v_add_co_u32_e32 v28, vcc, 0x2000, v44
	s_nop 1
	v_addc_co_u32_e32 v29, vcc, 0, v45, vcc
	v_cmp_gt_u32_e32 vcc, s37, v66
	global_store_dwordx4 v[28:29], v[24:27], off
	global_store_dwordx4 v[28:29], v[70:73], off offset:16
	s_and_saveexec_b64 s[4:5], vcc
	s_cbranch_execz .LBB0_144
	v_mul_f32_e32 v24, 0x3fb8aa3b, v56
	v_exp_f32_e32 v26, v24
	v_lshl_or_b32 v24, s40, 7, v66
	v_ashrrev_i32_e32 v25, 31, v24
	v_lshl_add_u64 v[24:25], v[24:25], 2, s[12:13]
	global_store_dword v[24:25], v26, off
.LBB0_144:
	s_or_b64 exec, exec, s[4:5]
	s_add_i32 s40, s40, s52
	s_cmpk_gt_i32 s40, 0x7ff
	s_cselect_b64 s[18:19], -1, 0
	s_and_b64 vcc, exec, s[18:19]
	s_waitcnt lgkmcnt(0)
	s_barrier
	s_cbranch_vccnz .LBB0_146
	s_lshl_b32 s4, s40, 3
	s_lshl_b32 s5, s40, 6
	s_and_b32 s4, s4, 0xfffff000
	s_and_b32 s5, s5, 0xfc0
	s_or_b32 s7, s4, s5
	v_or_b32_e32 v0, s7, v35
	v_mov_b64_e32 v[16:17], s[14:15]
	v_mad_i64_i32 v[0:1], s[4:5], v0, s3, v[16:17]
	v_ashrrev_i32_e32 v39, 31, v38
	s_lshl_b32 s4, s40, 2
	s_and_b32 s4, s4, 0x700
	s_mov_b32 s5, s9
	v_lshl_add_u64 v[0:1], v[38:39], 1, v[0:1]
	v_mov_b32_e32 v35, v33
	v_lshl_add_u64 v[0:1], v[0:1], 0, s[4:5]
	v_lshl_add_u64 v[18:19], v[0:1], 0, v[34:35]
	v_or_b32_e32 v0, s7, v41
	v_mad_i64_i32 v[0:1], s[16:17], v0, s3, v[16:17]
	v_ashrrev_i32_e32 v41, 31, v40
	v_lshl_add_u64 v[0:1], v[40:41], 1, v[0:1]
	v_add_co_u32_e32 v8, vcc, s24, v18
	v_lshl_add_u64 v[0:1], v[0:1], 0, s[4:5]
	s_nop 0
	v_addc_co_u32_e32 v9, vcc, 0, v19, vcc
	v_lshl_add_u64 v[0:1], v[0:1], 0, v[34:35]
	v_add_co_u32_e32 v20, vcc, s24, v0
	s_nop 1
	v_addc_co_u32_e32 v21, vcc, 0, v1, vcc
	global_load_dwordx4 v[4:7], v[8:9], off nt
	global_load_dwordx4 v[0:3], v[8:9], off offset:2048 nt
	v_or_b32_e32 v8, s7, v43
	v_mad_i64_i32 v[8:9], s[16:17], v8, s3, v[16:17]
	v_ashrrev_i32_e32 v43, 31, v42
	v_lshl_add_u64 v[8:9], v[42:43], 1, v[8:9]
	v_lshl_add_u64 v[8:9], v[8:9], 0, s[4:5]
	v_lshl_add_u64 v[8:9], v[8:9], 0, v[34:35]
	v_add_co_u32_e32 v22, vcc, s24, v8
	s_nop 1
	v_addc_co_u32_e32 v23, vcc, 0, v9, vcc
	v_add_co_u32_e32 v24, vcc, 0x2000, v18
	v_or_b32_e32 v18, s7, v37
	v_mad_i64_i32 v[16:17], s[16:17], v18, s3, v[16:17]
	v_ashrrev_i32_e32 v37, 31, v36
	v_lshl_add_u64 v[16:17], v[36:37], 1, v[16:17]
	v_lshl_add_u64 v[16:17], v[16:17], 0, s[4:5]
	v_addc_co_u32_e32 v25, vcc, 0, v19, vcc
	v_lshl_add_u64 v[16:17], v[16:17], 0, v[34:35]
	v_add_co_u32_e32 v26, vcc, 0x1000, v16
	global_load_dwordx4 v[8:11], v[20:21], off nt
	global_load_dwordx4 v[12:15], v[22:23], off nt
	v_addc_co_u32_e32 v27, vcc, 0, v17, vcc
	global_load_dwordx4 v[16:19], v[24:25], off nt
	global_load_dwordx4 v[20:23], v[26:27], off nt
	s_lshl_b32 s98, s40, 1
	s_and_b32 s98, s98, 0x380
	v_and_b32_e32 v202, 0x7f, v162
	v_or_b32_e32 v202, s98, v202
	v_lshlrev_b32_e32 v202, 2, v202
	v_add_u32_e32 v203, 0x1000, v202
	global_load_dword v200, v202, s[10:11]
	global_load_dword v201, v203, s[10:11]
